# adds on v90: in-proj and out K-loops with the remaining LDS read-address adds and DMA base setup hoisted in front of the loop (staging part without VALU)
# speedup vs baseline: 1.0028x; 1.0028x over previous
;     ...
;     const int aoff = lds_byte(wr * 64 + fr, fq * 8), boff = lds_byte(wc * 32 + fr, fq * 8);
.Lprio_skip_0:
	v_readfirstlane_b32 s100, v130
	v_readfirstlane_b32 s101, v131
	s_nop 1
	s_sub_u32 s100, s100, 0x10000000
	s_subb_u32 s101, s101, 0
	v_add_u32_e32 v216, 0x10000, v152
	v_add_u32_e32 v217, 0x14000, v152
	v_add_u32_e32 v218, 0x18000, v152
	v_add_u32_e32 v219, 0x1c000, v152

; #define PG8_STAGE(bufoff, gbase, voff) do { unsigned _g = (gbase); asm volatile("" : "+s"(_g));   _Pragma("unroll") for (int _i = 0; _i < 2; ++_i) \
;         __builtin_amdgcn_global_load_lds((const unsigned*)(wsb + (size_t)(unsigned)(_g + (voff)[_i])), (LAS unsigned*)(lds + (bufoff) + ldsw + _i * 8192), 16, 0, 0); } while (0)
; #define PG8_WAIT_V(n) asm volatile("s_waitcnt vmcnt(" #n ")" ::: "memory")
; #define PG8_WAIT_L(n) asm volatile("s_waitcnt lgkmcnt(" #n ")" ::: "memory")
; #define PG8_BAR __builtin_amdgcn_s_barrier()
; #define PG8_SCHED __builtin_amdgcn_sched_barrier(0)
;     ...
;             PG8_WAIT_V(8); PG8_WAIT_L(0); PG8_BAR; PG8_MMA(1, 0, At, B0); PG8_MMA(1, 1, At, B1); PG8_BAR; PG8_SCHED;
;             PG8_LDB(B0, 1, 0); PG8_LDB(B1, 1, 1); PG8_SCHED; PG8_LDA(At, 1, 0); PG8_STAGE(PG8_SA(0, 1), a2 + hstep, voffA);
.Lin_g1_join:
	s_waitcnt lgkmcnt(0)
	s_barrier
	s_waitcnt lgkmcnt(0)
	v_mfma_f32_16x16x32_bf16 v[62:65], v[138:141], v[178:181], v[62:65]
	v_mfma_f32_16x16x32_bf16 v[58:61], v[154:157], v[178:181], v[58:61]
	v_mfma_f32_16x16x32_bf16 v[46:49], v[138:141], v[186:189], v[46:49]
	v_mfma_f32_16x16x32_bf16 v[42:45], v[154:157], v[186:189], v[42:45]
	v_mfma_f32_16x16x32_bf16 v[30:33], v[138:141], v[194:197], v[30:33]
	v_mfma_f32_16x16x32_bf16 v[26:29], v[154:157], v[194:197], v[26:29]
	v_mfma_f32_16x16x32_bf16 v[14:17], v[138:141], v[202:205], v[14:17]
	v_mfma_f32_16x16x32_bf16 v[10:13], v[154:157], v[202:205], v[10:13]
	v_mfma_f32_16x16x32_bf16 v[62:65], v[142:145], v[182:185], v[62:65]
	v_mfma_f32_16x16x32_bf16 v[58:61], v[158:161], v[182:185], v[58:61]
	v_mfma_f32_16x16x32_bf16 v[46:49], v[142:145], v[190:193], v[46:49]
	v_mfma_f32_16x16x32_bf16 v[42:45], v[158:161], v[190:193], v[42:45]
	v_mfma_f32_16x16x32_bf16 v[30:33], v[142:145], v[198:201], v[30:33]
	v_mfma_f32_16x16x32_bf16 v[26:29], v[158:161], v[198:201], v[26:29]
	v_mfma_f32_16x16x32_bf16 v[14:17], v[142:145], v[206:209], v[14:17]
	v_mfma_f32_16x16x32_bf16 v[10:13], v[158:161], v[206:209], v[10:13]
	v_mfma_f32_16x16x32_bf16 v[54:57], v[162:165], v[178:181], v[54:57]
	v_mfma_f32_16x16x32_bf16 v[50:53], v[170:173], v[178:181], v[50:53]
	v_mfma_f32_16x16x32_bf16 v[38:41], v[162:165], v[186:189], v[38:41]
	v_mfma_f32_16x16x32_bf16 v[34:37], v[170:173], v[186:189], v[34:37]
	v_mfma_f32_16x16x32_bf16 v[22:25], v[162:165], v[194:197], v[22:25]
	v_mfma_f32_16x16x32_bf16 v[18:21], v[170:173], v[194:197], v[18:21]
	v_mfma_f32_16x16x32_bf16 v[6:9], v[162:165], v[202:205], v[6:9]
	v_mfma_f32_16x16x32_bf16 v[2:5], v[170:173], v[202:205], v[2:5]
	v_mfma_f32_16x16x32_bf16 v[54:57], v[166:169], v[182:185], v[54:57]
	v_mfma_f32_16x16x32_bf16 v[50:53], v[174:177], v[182:185], v[50:53]
	v_mfma_f32_16x16x32_bf16 v[38:41], v[166:169], v[190:193], v[38:41]
	v_mfma_f32_16x16x32_bf16 v[34:37], v[174:177], v[190:193], v[34:37]
	v_mfma_f32_16x16x32_bf16 v[22:25], v[166:169], v[198:201], v[22:25]
	v_mfma_f32_16x16x32_bf16 v[18:21], v[174:177], v[198:201], v[18:21]
	v_mfma_f32_16x16x32_bf16 v[6:9], v[166:169], v[206:209], v[6:9]
	v_mfma_f32_16x16x32_bf16 v[2:5], v[174:177], v[206:209], v[2:5]
	s_barrier
	s_add_i32 s84, 0, 0x18000
	s_add_i32 s96, 0, 0x1c000
	ds_read_b128 v[138:141], v218
	ds_read_b128 v[142:145], v218 offset:1024
	ds_read_b128 v[154:157], v218 offset:2048
	ds_read_b128 v[158:161], v218 offset:3072
	ds_read_b128 v[162:165], v219
	ds_read_b128 v[166:169], v219 offset:1024
	ds_read_b128 v[170:173], v219 offset:2048
	ds_read_b128 v[174:177], v219 offset:3072
	s_add_i32 s83, s83, 0x100000
	ds_read_b128 v[178:181], v153 offset:32768
	ds_read_b128 v[182:185], v153 offset:33792
	ds_read_b128 v[186:189], v153 offset:34816
	ds_read_b128 v[190:193], v153 offset:35840
	ds_read_b128 v[194:197], v153 offset:36864
	ds_read_b128 v[198:201], v153 offset:37888
	ds_read_b128 v[202:205], v153 offset:38912
	ds_read_b128 v[206:209], v153 offset:39936
	s_mov_b32 m0, s44
	s_add_i32 vcc_lo, s83, 0x10000000
	s_add_u32 vcc_lo, s100, vcc_lo
	s_addc_u32 vcc_hi, s101, 0
	global_load_lds_dwordx4 v148, vcc
	s_mov_b32 m0, s45
	s_nop 0
	global_load_lds_dwordx4 v150, vcc
	s_cmp_eq_i32 s10, -2
	s_cbranch_scc1 .Lin_g2_first

; #define PG8_STAGE(bufoff, gbase, voff) do { unsigned _g = (gbase); asm volatile("" : "+s"(_g));   _Pragma("unroll") for (int _i = 0; _i < 2; ++_i) \
;         __builtin_amdgcn_global_load_lds((const unsigned*)(wsb + (size_t)(unsigned)(_g + (voff)[_i])), (LAS unsigned*)(lds + (bufoff) + ldsw + _i * 8192), 16, 0, 0); } while (0)
; #define PG8_WAIT_V(n) asm volatile("s_waitcnt vmcnt(" #n ")" ::: "memory")
; #define PG8_WAIT_L(n) asm volatile("s_waitcnt lgkmcnt(" #n ")" ::: "memory")
; #define PG8_BAR __builtin_amdgcn_s_barrier()
; #define PG8_SCHED __builtin_amdgcn_sched_barrier(0)
;     ...
;             if constexpr (SP2) {
;             PG8_LDB(B0, 0, 0); PG8_LDB(B1, 0, 1); PG8_SCHED; PG8_LDA(At, 0, 0); PG8_STAGE(PG8_SA(1, 1), a1 + hstep, voffA);
;             PG8_WAIT_V(8); PG8_WAIT_L(0); PG8_BAR; PG8_MMA(0, 0, At, B0); PG8_MMA(0, 1, At, B1); PG8_BAR; PG8_SCHED;
;             PG8_LDA(At, 0, 1); PG8_STAGE(PG8_SB(0, 0), b2, voffB); PG8_STAGE(PG8_SB(0, 1), b2 + hstep, voffB); PG8_STAGE(PG8_SA(0, 0), a2, voffA);
;             PG8_WAIT_V(8); PG8_WAIT_L(0); PG8_BAR; PG8_MMA(1, 0, At, B0); PG8_MMA(1, 1, At, B1); PG8_BAR; PG8_SCHED;
.Lprio_skip_2:
	v_readfirstlane_b32 s100, v130
	v_readfirstlane_b32 s101, v131
	s_nop 1
	s_sub_u32 s100, s100, 0x10000000
	s_subb_u32 s101, s101, 0
	v_add_u32_e32 v216, 0x10000, v144
	v_add_u32_e32 v217, 0x14000, v144
	v_add_u32_e32 v218, 0x18000, v144
	v_add_u32_e32 v219, 0x1c000, v144
.LBB0_862:
	s_add_i32 s47, s10, 0xfff00080
	s_cmp_eq_u32 s18, 60
	s_cselect_b32 s83, s45, s47
	s_cselect_b32 s82, s46, s11
	s_add_i32 s84, 0, 0x10000
	s_waitcnt lgkmcnt(0)
	s_add_i32 s86, 0, 0x14000
	ds_read_b128 v[136:139], v216
	ds_read_b128 v[146:149], v216 offset:1024
	ds_read_b128 v[150:153], v216 offset:2048
	ds_read_b128 v[154:157], v216 offset:3072
	ds_read_b128 v[158:161], v217
	ds_read_b128 v[162:165], v217 offset:1024
	ds_read_b128 v[166:169], v217 offset:2048
	ds_read_b128 v[170:173], v217 offset:3072
	s_add_i32 s47, s83, 0x80
	s_mov_b32 s87, s10
	ds_read_b128 v[174:177], v145
	ds_read_b128 v[178:181], v145 offset:1024
	ds_read_b128 v[182:185], v145 offset:2048
	ds_read_b128 v[186:189], v145 offset:3072
	ds_read_b128 v[190:193], v145 offset:4096
	ds_read_b128 v[194:197], v145 offset:5120
	ds_read_b128 v[198:201], v145 offset:6144
	ds_read_b128 v[202:205], v145 offset:7168
	s_add_i32 m0, s22, 0xc000
	s_add_i32 vcc_lo, s87, 0x10000000
	s_add_u32 vcc_lo, s100, vcc_lo
	s_addc_u32 vcc_hi, s101, 0
	global_load_lds_dwordx4 v140, vcc
	s_add_i32 m0, s22, 0xe000
	s_nop 0
	global_load_lds_dwordx4 v142, vcc
	s_waitcnt vmcnt(8)
	s_waitcnt lgkmcnt(0)
	s_barrier
	s_waitcnt lgkmcnt(0)
	v_mfma_f32_16x16x32_bf16 v[126:129], v[136:139], v[174:177], v[126:129]
	v_mfma_f32_16x16x32_bf16 v[122:125], v[150:153], v[174:177], v[122:125]
	v_mfma_f32_16x16x32_bf16 v[110:113], v[136:139], v[182:185], v[110:113]
	v_mfma_f32_16x16x32_bf16 v[106:109], v[150:153], v[182:185], v[106:109]
	v_mfma_f32_16x16x32_bf16 v[94:97], v[136:139], v[190:193], v[94:97]
	v_mfma_f32_16x16x32_bf16 v[90:93], v[150:153], v[190:193], v[90:93]
	v_mfma_f32_16x16x32_bf16 v[78:81], v[136:139], v[198:201], v[78:81]
	v_mfma_f32_16x16x32_bf16 v[74:77], v[150:153], v[198:201], v[74:77]
	v_mfma_f32_16x16x32_bf16 v[126:129], v[146:149], v[178:181], v[126:129]
	v_mfma_f32_16x16x32_bf16 v[122:125], v[154:157], v[178:181], v[122:125]
	v_mfma_f32_16x16x32_bf16 v[110:113], v[146:149], v[186:189], v[110:113]
	v_mfma_f32_16x16x32_bf16 v[106:109], v[154:157], v[186:189], v[106:109]
	v_mfma_f32_16x16x32_bf16 v[94:97], v[146:149], v[194:197], v[94:97]
	v_mfma_f32_16x16x32_bf16 v[90:93], v[154:157], v[194:197], v[90:93]
	v_mfma_f32_16x16x32_bf16 v[78:81], v[146:149], v[202:205], v[78:81]
	v_mfma_f32_16x16x32_bf16 v[74:77], v[154:157], v[202:205], v[74:77]
	v_mfma_f32_16x16x32_bf16 v[118:121], v[158:161], v[174:177], v[118:121]
	v_mfma_f32_16x16x32_bf16 v[114:117], v[166:169], v[174:177], v[114:117]
	v_mfma_f32_16x16x32_bf16 v[102:105], v[158:161], v[182:185], v[102:105]
	v_mfma_f32_16x16x32_bf16 v[98:101], v[166:169], v[182:185], v[98:101]
	v_mfma_f32_16x16x32_bf16 v[86:89], v[158:161], v[190:193], v[86:89]
	v_mfma_f32_16x16x32_bf16 v[82:85], v[166:169], v[190:193], v[82:85]
	v_mfma_f32_16x16x32_bf16 v[70:73], v[158:161], v[198:201], v[70:73]
	v_mfma_f32_16x16x32_bf16 v[66:69], v[166:169], v[198:201], v[66:69]
	v_mfma_f32_16x16x32_bf16 v[118:121], v[162:165], v[178:181], v[118:121]
	v_mfma_f32_16x16x32_bf16 v[114:117], v[170:173], v[178:181], v[114:117]
	v_mfma_f32_16x16x32_bf16 v[102:105], v[162:165], v[186:189], v[102:105]
	v_mfma_f32_16x16x32_bf16 v[98:101], v[170:173], v[186:189], v[98:101]
	v_mfma_f32_16x16x32_bf16 v[86:89], v[162:165], v[194:197], v[86:89]
	v_mfma_f32_16x16x32_bf16 v[82:85], v[170:173], v[194:197], v[82:85]
	v_mfma_f32_16x16x32_bf16 v[70:73], v[162:165], v[202:205], v[70:73]
	v_mfma_f32_16x16x32_bf16 v[66:69], v[170:173], v[202:205], v[66:69]
	s_barrier
	s_mov_b32 s87, s82
	ds_read_b128 v[174:177], v145 offset:16384
	ds_read_b128 v[178:181], v145 offset:17408
	ds_read_b128 v[182:185], v145 offset:18432
	ds_read_b128 v[186:189], v145 offset:19456
	ds_read_b128 v[190:193], v145 offset:20480
	ds_read_b128 v[194:197], v145 offset:21504
	ds_read_b128 v[198:201], v145 offset:22528
	ds_read_b128 v[202:205], v145 offset:23552
	s_add_i32 s84, s84, s7
	s_add_i32 vcc_lo, s87, 0x10000000
	s_add_u32 vcc_lo, s100, vcc_lo
	s_addc_u32 vcc_hi, s101, 0
	s_mov_b32 m0, s84
	s_nop 0
	global_load_lds_dwordx4 v141, vcc
	s_add_i32 m0, s84, 0x2000
	s_add_i32 s84, s82, 0x100000
	global_load_lds_dwordx4 v143, vcc
	s_add_i32 s86, s86, s7
	s_add_i32 vcc_lo, s84, 0x10000000
	s_add_u32 vcc_lo, s100, vcc_lo
	s_addc_u32 vcc_hi, s101, 0
	s_mov_b32 m0, s86
	s_nop 0
	global_load_lds_dwordx4 v141, vcc
	s_add_i32 m0, s86, 0x2000
	s_mov_b32 s84, s83
	global_load_lds_dwordx4 v143, vcc
	s_mov_b32 m0, s22
	s_add_i32 vcc_lo, s84, 0x10000000
	s_add_u32 vcc_lo, s100, vcc_lo
	s_addc_u32 vcc_hi, s101, 0
	global_load_lds_dwordx4 v140, vcc
	s_mov_b32 m0, s23
	s_nop 0
	global_load_lds_dwordx4 v142, vcc
	s_waitcnt vmcnt(8)
	s_waitcnt lgkmcnt(0)
	s_barrier
; #define PG8_STAGE(bufoff, gbase, voff) do { unsigned _g = (gbase); asm volatile("" : "+s"(_g));   _Pragma("unroll") for (int _i = 0; _i < 2; ++_i) \
;         __builtin_amdgcn_global_load_lds((const unsigned*)(wsb + (size_t)(unsigned)(_g + (voff)[_i])), (LAS unsigned*)(lds + (bufoff) + ldsw + _i * 8192), 16, 0, 0); } while (0)
; #define PG8_WAIT_V(n) asm volatile("s_waitcnt vmcnt(" #n ")" ::: "memory")
; #define PG8_WAIT_L(n) asm volatile("s_waitcnt lgkmcnt(" #n ")" ::: "memory")
; #define PG8_BAR __builtin_amdgcn_s_barrier()
; #define PG8_SCHED __builtin_amdgcn_sched_barrier(0)
;     ...
;             PG8_WAIT_V(8); PG8_WAIT_L(0); PG8_BAR; PG8_MMA(1, 0, At, B0); PG8_MMA(1, 1, At, B1); PG8_BAR; PG8_SCHED;
;             PG8_LDB(B0, 1, 0); PG8_LDB(B1, 1, 1); PG8_SCHED; PG8_LDA(At, 1, 0); PG8_STAGE(PG8_SA(0, 1), a2 + hstep, voffA);
;             PG8_WAIT_V(8); PG8_WAIT_L(0); PG8_BAR; PG8_MMA(0, 0, At, B0); PG8_MMA(0, 1, At, B1); PG8_BAR; PG8_SCHED;
;             PG8_LDA(At, 1, 1); PG8_STAGE(PG8_SB(1, 0), b3, voffB); PG8_STAGE(PG8_SB(1, 1), b3 + hstep, voffB); PG8_STAGE(PG8_SA(1, 0), a3, voffA);
	s_waitcnt lgkmcnt(0)
	v_mfma_f32_16x16x32_bf16 v[62:65], v[136:139], v[174:177], v[62:65]
	v_mfma_f32_16x16x32_bf16 v[58:61], v[150:153], v[174:177], v[58:61]
	v_mfma_f32_16x16x32_bf16 v[46:49], v[136:139], v[182:185], v[46:49]
	v_mfma_f32_16x16x32_bf16 v[42:45], v[150:153], v[182:185], v[42:45]
	v_mfma_f32_16x16x32_bf16 v[30:33], v[136:139], v[190:193], v[30:33]
	v_mfma_f32_16x16x32_bf16 v[26:29], v[150:153], v[190:193], v[26:29]
	v_mfma_f32_16x16x32_bf16 v[14:17], v[136:139], v[198:201], v[14:17]
	v_mfma_f32_16x16x32_bf16 v[10:13], v[150:153], v[198:201], v[10:13]
	v_mfma_f32_16x16x32_bf16 v[62:65], v[146:149], v[178:181], v[62:65]
	v_mfma_f32_16x16x32_bf16 v[58:61], v[154:157], v[178:181], v[58:61]
	v_mfma_f32_16x16x32_bf16 v[46:49], v[146:149], v[186:189], v[46:49]
	v_mfma_f32_16x16x32_bf16 v[42:45], v[154:157], v[186:189], v[42:45]
	v_mfma_f32_16x16x32_bf16 v[30:33], v[146:149], v[194:197], v[30:33]
	v_mfma_f32_16x16x32_bf16 v[26:29], v[154:157], v[194:197], v[26:29]
	v_mfma_f32_16x16x32_bf16 v[14:17], v[146:149], v[202:205], v[14:17]
	v_mfma_f32_16x16x32_bf16 v[10:13], v[154:157], v[202:205], v[10:13]
	v_mfma_f32_16x16x32_bf16 v[54:57], v[158:161], v[174:177], v[54:57]
	v_mfma_f32_16x16x32_bf16 v[50:53], v[166:169], v[174:177], v[50:53]
	v_mfma_f32_16x16x32_bf16 v[38:41], v[158:161], v[182:185], v[38:41]
	v_mfma_f32_16x16x32_bf16 v[34:37], v[166:169], v[182:185], v[34:37]
	v_mfma_f32_16x16x32_bf16 v[22:25], v[158:161], v[190:193], v[22:25]
	v_mfma_f32_16x16x32_bf16 v[18:21], v[166:169], v[190:193], v[18:21]
	v_mfma_f32_16x16x32_bf16 v[6:9], v[158:161], v[198:201], v[6:9]
	v_mfma_f32_16x16x32_bf16 v[2:5], v[166:169], v[198:201], v[2:5]
	v_mfma_f32_16x16x32_bf16 v[54:57], v[162:165], v[178:181], v[54:57]
	v_mfma_f32_16x16x32_bf16 v[50:53], v[170:173], v[178:181], v[50:53]
	v_mfma_f32_16x16x32_bf16 v[38:41], v[162:165], v[186:189], v[38:41]
	v_mfma_f32_16x16x32_bf16 v[34:37], v[170:173], v[186:189], v[34:37]
	v_mfma_f32_16x16x32_bf16 v[22:25], v[162:165], v[194:197], v[22:25]
	v_mfma_f32_16x16x32_bf16 v[18:21], v[170:173], v[194:197], v[18:21]
	v_mfma_f32_16x16x32_bf16 v[6:9], v[162:165], v[202:205], v[6:9]
	v_mfma_f32_16x16x32_bf16 v[2:5], v[170:173], v[202:205], v[2:5]
	s_barrier
	s_add_i32 s84, 0, 0x18000
	s_add_i32 s86, 0, 0x1c000
	ds_read_b128 v[136:139], v218
	ds_read_b128 v[146:149], v218 offset:1024
	ds_read_b128 v[150:153], v218 offset:2048
	ds_read_b128 v[154:157], v218 offset:3072
	ds_read_b128 v[158:161], v219
	ds_read_b128 v[162:165], v219 offset:1024
	ds_read_b128 v[166:169], v219 offset:2048
	ds_read_b128 v[170:173], v219 offset:3072
	s_add_i32 s83, s83, 0x100000
	ds_read_b128 v[174:177], v145 offset:32768
	ds_read_b128 v[178:181], v145 offset:33792
	ds_read_b128 v[182:185], v145 offset:34816
	ds_read_b128 v[186:189], v145 offset:35840
	ds_read_b128 v[190:193], v145 offset:36864
	ds_read_b128 v[194:197], v145 offset:37888
	ds_read_b128 v[198:201], v145 offset:38912
	ds_read_b128 v[202:205], v145 offset:39936
	s_mov_b32 m0, s24
	s_add_i32 vcc_lo, s83, 0x10000000
	s_add_u32 vcc_lo, s100, vcc_lo
	s_addc_u32 vcc_hi, s101, 0
	global_load_lds_dwordx4 v140, vcc
	s_mov_b32 m0, s25
	s_nop 0
	global_load_lds_dwordx4 v142, vcc
	s_waitcnt vmcnt(8)
	s_waitcnt lgkmcnt(0)
	s_barrier
	s_waitcnt lgkmcnt(0)
	v_mfma_f32_16x16x32_bf16 v[126:129], v[136:139], v[174:177], v[126:129]
	v_mfma_f32_16x16x32_bf16 v[122:125], v[150:153], v[174:177], v[122:125]
	v_mfma_f32_16x16x32_bf16 v[110:113], v[136:139], v[182:185], v[110:113]
	v_mfma_f32_16x16x32_bf16 v[106:109], v[150:153], v[182:185], v[106:109]
	v_mfma_f32_16x16x32_bf16 v[94:97], v[136:139], v[190:193], v[94:97]
	v_mfma_f32_16x16x32_bf16 v[90:93], v[150:153], v[190:193], v[90:93]
	v_mfma_f32_16x16x32_bf16 v[78:81], v[136:139], v[198:201], v[78:81]
	v_mfma_f32_16x16x32_bf16 v[74:77], v[150:153], v[198:201], v[74:77]
	v_mfma_f32_16x16x32_bf16 v[126:129], v[146:149], v[178:181], v[126:129]
	v_mfma_f32_16x16x32_bf16 v[122:125], v[154:157], v[178:181], v[122:125]
	v_mfma_f32_16x16x32_bf16 v[110:113], v[146:149], v[186:189], v[110:113]
	v_mfma_f32_16x16x32_bf16 v[106:109], v[154:157], v[186:189], v[106:109]
	v_mfma_f32_16x16x32_bf16 v[94:97], v[146:149], v[194:197], v[94:97]
	v_mfma_f32_16x16x32_bf16 v[90:93], v[154:157], v[194:197], v[90:93]
	v_mfma_f32_16x16x32_bf16 v[78:81], v[146:149], v[202:205], v[78:81]
	v_mfma_f32_16x16x32_bf16 v[74:77], v[154:157], v[202:205], v[74:77]
	v_mfma_f32_16x16x32_bf16 v[118:121], v[158:161], v[174:177], v[118:121]
	v_mfma_f32_16x16x32_bf16 v[114:117], v[166:169], v[174:177], v[114:117]
	v_mfma_f32_16x16x32_bf16 v[102:105], v[158:161], v[182:185], v[102:105]
	v_mfma_f32_16x16x32_bf16 v[98:101], v[166:169], v[182:185], v[98:101]
	v_mfma_f32_16x16x32_bf16 v[86:89], v[158:161], v[190:193], v[86:89]
	v_mfma_f32_16x16x32_bf16 v[82:85], v[166:169], v[190:193], v[82:85]
	v_mfma_f32_16x16x32_bf16 v[70:73], v[158:161], v[198:201], v[70:73]
	v_mfma_f32_16x16x32_bf16 v[66:69], v[166:169], v[198:201], v[66:69]
	v_mfma_f32_16x16x32_bf16 v[118:121], v[162:165], v[178:181], v[118:121]
	v_mfma_f32_16x16x32_bf16 v[114:117], v[170:173], v[178:181], v[114:117]
	v_mfma_f32_16x16x32_bf16 v[102:105], v[162:165], v[186:189], v[102:105]
	v_mfma_f32_16x16x32_bf16 v[98:101], v[170:173], v[186:189], v[98:101]
	v_mfma_f32_16x16x32_bf16 v[86:89], v[162:165], v[194:197], v[86:89]
	v_mfma_f32_16x16x32_bf16 v[82:85], v[170:173], v[194:197], v[82:85]
	v_mfma_f32_16x16x32_bf16 v[70:73], v[162:165], v[202:205], v[70:73]
	v_mfma_f32_16x16x32_bf16 v[66:69], v[170:173], v[202:205], v[66:69]
	s_barrier
; #define GAS __attribute__((address_space(1)))
; __device__ __forceinline__ unsigned cvt_pk_bf16(float lo, float hi) { const f32x2_t_ v = {lo, hi}; const bf16x2_t_ b = __builtin_convertvector(v, bf16x2_t_); return __builtin_bit_cast(unsigned, b); }
; #define PG8_STAGE(bufoff, gbase, voff) do { unsigned _g = (gbase); asm volatile("" : "+s"(_g));   _Pragma("unroll") for (int _i = 0; _i < 2; ++_i) \
;         __builtin_amdgcn_global_load_lds((const unsigned*)(wsb + (size_t)(unsigned)(_g + (voff)[_i])), (LAS unsigned*)(lds + (bufoff) + ldsw + _i * 8192), 16, 0, 0); } while (0)
; #define PG8_WAIT_V(n) asm volatile("s_waitcnt vmcnt(" #n ")" ::: "memory")
; #define PG8_WAIT_L(n) asm volatile("s_waitcnt lgkmcnt(" #n ")" ::: "memory")
; #define PG8_BAR __builtin_amdgcn_s_barrier()
; #define PG8_SCHED __builtin_amdgcn_sched_barrier(0)
;     ...
;             PG8_LDA(At, 1, 1); PG8_STAGE(PG8_SB(1, 0), b3, voffB); PG8_STAGE(PG8_SB(1, 1), b3 + hstep, voffB); PG8_STAGE(PG8_SA(1, 0), a3, voffA);
;             PG8_WAIT_V(8); PG8_WAIT_L(0); PG8_BAR; PG8_MMA(1, 0, At, B0); PG8_MMA(1, 1, At, B1); PG8_BAR; PG8_SCHED;
;     __device__ __forceinline__ void operator()(const f32x4 (&acc)[2][2][4][2], const pg8::GUnit& u, int wr, int wc, int fr, int fq) const {
;         const int row0 = u.pm * 256 + wr * 64 + fr, col0 = u.pn * 256 + wc * 32 + 8 * fq;
; #pragma unroll
;         for (int ai = 0; ai < 2; ++ai)
; #pragma unroll
;             for (int m = 0; m < 4; ++m) { const size_t row = (size_t)(row0 + ai * 128 + m * 16); float s = 0.f;
; #pragma unroll
;                 for (int bj = 0; bj < 2; ++bj) { const f32x4 v0 = acc[ai][bj][m][0], v1 = acc[ai][bj][m][1];
;                     s += (v0[0] * v0[0] + v0[1] * v0[1]) + (v0[2] * v0[2] + v0[3] * v0[3]) + (v1[0] * v1[0] + v1[1] * v1[1]) + (v1[2] * v1[2] + v1[3] * v1[3]);
;                     u32x4 w; w.x = cvt_pk_bf16(v0[0], v0[1]); w.y = cvt_pk_bf16(v0[2], v0[3]); w.z = cvt_pk_bf16(v1[0], v1[1]); w.w = cvt_pk_bf16(v1[2], v1[3]);
;                     *(GAS u32x4*)((GAS bf16_t*)O + row * DM + col0 + bj * 128) = w; }
;                 { const int ln = fr + 16 * fq; s += __int_as_float(__builtin_amdgcn_ds_bpermute((ln ^ 16) << 2, __float_as_int(s))); s += __int_as_float(__builtin_amdgcn_ds_bpermute((ln ^ 32) << 2, __float_as_int(s))); }
;                 if (fq == 0) ((GAS float*)RSQ)[row * 64 + u.pn * 4 + wc] = s; }
	s_add_i32 s83, s82, 0x80
	ds_read_b128 v[174:177], v145 offset:49152
	ds_read_b128 v[178:181], v145 offset:50176
	ds_read_b128 v[182:185], v145 offset:51200
	ds_read_b128 v[186:189], v145 offset:52224
	ds_read_b128 v[190:193], v145 offset:53248
	ds_read_b128 v[194:197], v145 offset:54272
	ds_read_b128 v[198:201], v145 offset:55296
	ds_read_b128 v[202:205], v145 offset:56320
	s_add_i32 s84, s84, s7
	s_add_i32 vcc_lo, s83, 0x10000000
	s_add_u32 vcc_lo, s100, vcc_lo
	s_addc_u32 vcc_hi, s101, 0
	s_mov_b32 m0, s84
	s_nop 0
	global_load_lds_dwordx4 v141, vcc
	s_add_i32 m0, s84, 0x2000
	s_add_i32 s82, s82, 0x100080
	global_load_lds_dwordx4 v143, vcc
	s_add_i32 s83, s86, s7
	s_add_i32 vcc_lo, s82, 0x10000000
	s_add_u32 vcc_lo, s100, vcc_lo
	s_addc_u32 vcc_hi, s101, 0
	s_mov_b32 m0, s83
	s_nop 0
	global_load_lds_dwordx4 v141, vcc
	s_add_i32 m0, s83, 0x2000
	s_nop 0
	global_load_lds_dwordx4 v143, vcc
	s_mov_b32 m0, s36
	s_add_i32 vcc_lo, s47, 0x10000000
	s_add_u32 vcc_lo, s100, vcc_lo
	s_addc_u32 vcc_hi, s101, 0
	global_load_lds_dwordx4 v140, vcc
	s_mov_b32 m0, s37
	s_nop 0
	global_load_lds_dwordx4 v142, vcc
	s_waitcnt vmcnt(8)
	s_waitcnt lgkmcnt(0)
	s_barrier
	s_waitcnt lgkmcnt(0)
	v_mfma_f32_16x16x32_bf16 v[62:65], v[136:139], v[174:177], v[62:65]
	v_mfma_f32_16x16x32_bf16 v[58:61], v[150:153], v[174:177], v[58:61]
	v_mfma_f32_16x16x32_bf16 v[46:49], v[136:139], v[182:185], v[46:49]
	v_mfma_f32_16x16x32_bf16 v[42:45], v[150:153], v[182:185], v[42:45]
	v_mfma_f32_16x16x32_bf16 v[30:33], v[136:139], v[190:193], v[30:33]
	v_mfma_f32_16x16x32_bf16 v[26:29], v[150:153], v[190:193], v[26:29]
	v_mfma_f32_16x16x32_bf16 v[14:17], v[136:139], v[198:201], v[14:17]
	v_mfma_f32_16x16x32_bf16 v[10:13], v[150:153], v[198:201], v[10:13]
	v_mfma_f32_16x16x32_bf16 v[62:65], v[146:149], v[178:181], v[62:65]
	v_mfma_f32_16x16x32_bf16 v[58:61], v[154:157], v[178:181], v[58:61]
	v_mfma_f32_16x16x32_bf16 v[46:49], v[146:149], v[186:189], v[46:49]
	v_mfma_f32_16x16x32_bf16 v[42:45], v[154:157], v[186:189], v[42:45]
	v_mfma_f32_16x16x32_bf16 v[30:33], v[146:149], v[194:197], v[30:33]
	v_mfma_f32_16x16x32_bf16 v[26:29], v[154:157], v[194:197], v[26:29]
	v_mfma_f32_16x16x32_bf16 v[14:17], v[146:149], v[202:205], v[14:17]
	v_mfma_f32_16x16x32_bf16 v[10:13], v[154:157], v[202:205], v[10:13]
	v_mfma_f32_16x16x32_bf16 v[54:57], v[158:161], v[174:177], v[54:57]
	v_mfma_f32_16x16x32_bf16 v[50:53], v[166:169], v[174:177], v[50:53]
	v_mfma_f32_16x16x32_bf16 v[38:41], v[158:161], v[182:185], v[38:41]
	v_mfma_f32_16x16x32_bf16 v[34:37], v[166:169], v[182:185], v[34:37]
	v_mfma_f32_16x16x32_bf16 v[22:25], v[158:161], v[190:193], v[22:25]
	v_mfma_f32_16x16x32_bf16 v[18:21], v[166:169], v[190:193], v[18:21]
	v_mfma_f32_16x16x32_bf16 v[6:9], v[158:161], v[198:201], v[6:9]
	v_mfma_f32_16x16x32_bf16 v[2:5], v[166:169], v[198:201], v[2:5]
	v_mfma_f32_16x16x32_bf16 v[54:57], v[162:165], v[178:181], v[54:57]
	v_mfma_f32_16x16x32_bf16 v[50:53], v[170:173], v[178:181], v[50:53]
	v_mfma_f32_16x16x32_bf16 v[38:41], v[162:165], v[186:189], v[38:41]
	v_mfma_f32_16x16x32_bf16 v[34:37], v[170:173], v[186:189], v[34:37]
	v_mfma_f32_16x16x32_bf16 v[22:25], v[162:165], v[194:197], v[22:25]
	v_mfma_f32_16x16x32_bf16 v[18:21], v[170:173], v[194:197], v[18:21]
	v_mfma_f32_16x16x32_bf16 v[6:9], v[162:165], v[202:205], v[6:9]
	v_mfma_f32_16x16x32_bf16 v[2:5], v[170:173], v[202:205], v[2:5]
	s_barrier
	s_add_i32 s18, s18, 2
	s_addk_i32 s10, 0x100
	s_addk_i32 s11, 0x100
	s_cmp_gt_u32 s18, 61
	s_cbranch_scc0 .LBB0_862
	s_setprio 0
	s_lshl_b32 s9, s9, 8
	v_mbcnt_lo_u32_b32 v139, -1, 0
	v_mbcnt_hi_u32_b32 v139, -1, v139
	s_add_i32 s9, s9, s3
	v_and_b32_e32 v0, 15, v139
	v_ashrrev_i32_e32 v146, 4, v139
	v_or_b32_e32 v138, s9, v0
	s_lshl_b32 s9, s8, 8
	s_or_b32 s9, s9, s88
	v_lshlrev_b32_e32 v147, 6, v146
	v_lshlrev_b32_e32 v0, 2, v0
	v_lshl_add_u32 v136, v146, 3, s9
	v_bitop3_b32 v146, v147, 64, v0 bitop3:0x36
	v_bitop3_b32 v0, v147, s92, v0 bitop3:0x36
	v_mul_f32_e32 v147, v127, v127
	v_mul_f32_e32 v150, v129, v129
	v_fmac_f32_e32 v147, v126, v126
	v_fmac_f32_e32 v150, v128, v128
	v_add_f32_e32 v147, v147, v150
	v_mul_f32_e32 v150, v123, v123
	v_fmac_f32_e32 v150, v122, v122
	v_cvt_pk_bf16_f32 v126, v126, v127
	v_cvt_pk_bf16_f32 v127, v128, v129
	v_cvt_pk_bf16_f32 v128, v122, v123
	v_mul_f32_e32 v122, v119, v119
	v_mul_f32_e32 v123, v121, v121
	v_fmac_f32_e32 v122, v118, v118
	v_fmac_f32_e32 v123, v120, v120
	v_add_f32_e32 v122, v122, v123
	v_mul_f32_e32 v123, v115, v115
	v_fmac_f32_e32 v123, v114, v114
	v_add_f32_e32 v147, v147, v150
	v_mul_f32_e32 v150, v125, v125
	v_add_f32_e32 v122, v122, v123
	v_mul_f32_e32 v123, v117, v117
	v_fmac_f32_e32 v150, v124, v124
	v_fmac_f32_e32 v123, v116, v116
	v_add_f32_e32 v147, v150, v147
	v_add_f32_e32 v122, v123, v122
	v_cvt_pk_bf16_f32 v129, v124, v125
	v_add_f32_e32 v124, v147, v122
	ds_bpermute_b32 v125, v146, v124
	v_cmp_gt_u32_e32 vcc, 16, v139
	v_ashrrev_i32_e32 v139, 31, v138
	v_lshlrev_b64 v[148:149], 13, v[138:139]
	v_ashrrev_i32_e32 v137, 31, v136
	v_lshl_add_u64 v[122:123], v[132:133], 0, v[148:149]
	v_lshl_add_u64 v[148:149], v[136:137], 1, v[122:123]
	v_cvt_pk_bf16_f32 v122, v118, v119
	s_waitcnt lgkmcnt(0)
	v_add_f32_e32 v118, v124, v125
	ds_bpermute_b32 v119, v0, v118
	s_lshl_b32 s8, s8, 2
	s_ashr_i32 s9, s8, 31
	v_cvt_pk_bf16_f32 v123, v120, v121
	v_cvt_pk_bf16_f32 v124, v114, v115
	v_cvt_pk_bf16_f32 v125, v116, v117
	global_store_dwordx4 v[148:149], v[126:129], off
	global_store_dwordx4 v[148:149], v[122:125], off offset:256
	s_and_saveexec_b64 s[10:11], vcc
	s_cbranch_execz .LBB0_865
	v_lshlrev_b64 v[114:115], 8, v[138:139]
	v_lshl_add_u64 v[114:115], v[134:135], 0, v[114:115]
	v_lshl_add_u64 v[114:115], s[8:9], 2, v[114:115]
	s_lshl_b32 s18, s43, 2
	s_waitcnt lgkmcnt(0)
	v_add_f32_e32 v116, v118, v119
	v_lshl_add_u64 v[114:115], v[114:115], 0, s[18:19]
	global_store_dword v[114:115], v116, off
